# strategy 10: prep level-2 block-inverse stages (two 32x32x32 f32 products per item) on v_mfma_f32_16x16x4_f32 (exact k-ordered f32 fma chain) instead of LDS-fed per-thread v_fmac chains
# speedup vs baseline: 1.0059x; 1.0003x over previous
; #define LDS_BARRIER() do { asm volatile("s_waitcnt lgkmcnt(0)" ::: "memory"); __builtin_amdgcn_s_barrier(); asm volatile("" ::: "memory"); } while (0)
; __device__ __forceinline__ void phase_dnprep(h16* Pdn, const h16* halo, const float* bd, const float* convw, const float* a_log, const float* dt_bias,
;                              h16* Tg, h16* qkg, float* gcg, float* betag, float* s2g, LAS unsigned char* ldsl, unsigned char* ldsb) {
;     ...
;         {
;             const int which = tl >> 8, r = (tl >> 4) & 15, c = tl & 15, rb = which ? 48 : 16, cb = which ? 32 : 0;
;             float sacc = 0.f;
; #pragma unroll
;             for (int k = 0; k < 16; ++k) sacc += Mm[(rb + r) * 68 + cb + k] * X[(cb + k) * 68 + cb + c];
;             Zs[(which * 16 + r) * 17 + c] = sacc;
;         }
;         LDS_BARRIER();
;         {
;             const int which = tl >> 8, r = (tl >> 4) & 15, c = tl & 15, rb = which ? 48 : 16, cb = which ? 32 : 0;
;             float sacc = 0.f;
; #pragma unroll
;             for (int m = 0; m < 16; ++m) sacc += X[(rb + r) * 68 + rb + m] * Zs[(which * 16 + m) * 17 + c];
;             X[(rb + r) * 68 + cb + c] = -sacc;
;         }
.LBB0_320:
	s_or_b64 exec, exec, s[0:1]
	s_movk_i32 s0, 0x100
	v_cmp_gt_u32_e32 vcc, s0, v82
	v_bfe_u32 v0, v82, 4, 4
	v_lshlrev_b32_e32 v27, 2, v100
	v_cndmask_b32_e64 v22, 48, 16, vcc
	v_cndmask_b32_e64 v1, 32, 0, vcc
	v_or_b32_e32 v23, v22, v0
	v_mul_u32_u24_e32 v0, 0x110, v23
	v_lshlrev_b32_e32 v26, 2, v1
	v_add3_u32 v12, s3, v0, v26
	v_mul_u32_u24_e32 v0, 0x110, v1
	v_add_u32_e32 v16, s78, v27
	s_waitcnt lgkmcnt(0)
	s_barrier
	v_add3_u32 v24, v16, v26, v0
	ds_read2_b32 v[18:19], v24 offset1:68
	ds_read_b128 v[0:3], v12
	ds_read_b128 v[4:7], v12 offset:16
	ds_read2_b32 v[20:21], v24 offset0:136 offset1:204
	ds_read_b128 v[8:11], v12 offset:32
	ds_read_b128 v[12:15], v12 offset:48
	s_waitcnt lgkmcnt(4)
	v_fma_f32 v25, v0, v18, 0
	v_fmac_f32_e32 v25, v1, v19
	s_waitcnt lgkmcnt(2)
	v_fmac_f32_e32 v25, v2, v20
	v_add_u32_e32 v2, 0x400, v24
	ds_read2_b32 v[0:1], v2 offset0:16 offset1:84
	v_fmac_f32_e32 v25, v3, v21
	ds_read2_b32 v[2:3], v2 offset0:152 offset1:220
	v_add_u32_e32 v20, 0x800, v24
	ds_read2_b32 v[18:19], v20 offset0:32 offset1:100
	s_waitcnt lgkmcnt(2)
	v_fmac_f32_e32 v25, v4, v0
	v_fmac_f32_e32 v25, v5, v1
	ds_read2_b32 v[0:1], v20 offset0:168 offset1:236
	s_waitcnt lgkmcnt(2)
	v_fmac_f32_e32 v25, v6, v2
	v_add_u32_e32 v4, 0xc00, v24
	v_fmac_f32_e32 v25, v7, v3
	ds_read2_b32 v[2:3], v4 offset0:48 offset1:116
	s_waitcnt lgkmcnt(2)
	v_fmac_f32_e32 v25, v8, v18
	v_fmac_f32_e32 v25, v9, v19
	ds_read2_b32 v[4:5], v4 offset0:184 offset1:252
	s_waitcnt lgkmcnt(2)
	v_fmac_f32_e32 v25, v10, v0
	v_fmac_f32_e32 v25, v11, v1
	s_waitcnt lgkmcnt(1)
	v_fmac_f32_e32 v25, v12, v2
	v_lshrrev_b32_e32 v17, 4, v82
	v_fmac_f32_e32 v25, v13, v3
	v_ashrrev_i32_e32 v28, 4, v82
	s_waitcnt lgkmcnt(0)
	v_fmac_f32_e32 v25, v14, v4
	v_bfi_b32 v0, -16, v28, v17
	s_movk_i32 s5, 0x44
	v_fmac_f32_e32 v25, v15, v5
	v_mad_u64_u32 v[0:1], s[0:1], v0, s5, v[16:17]
	ds_write_b32 v0, v25 offset:17408
	v_mov_b32_e32 v0, s78
	s_movk_i32 s4, 0x110
	v_and_b32_e32 v2, -16, v28
	v_mad_u32_u24 v17, v23, s4, v0
	v_mad_u64_u32 v[18:19], s[0:1], v2, s5, v[16:17]
	s_waitcnt lgkmcnt(0)
	s_barrier
	v_lshl_add_u32 v12, v22, 2, v17
	v_add_u32_e32 v19, 0x4400, v18
	ds_read2_b32 v[20:21], v19 offset1:17
	ds_read_b128 v[0:3], v12
	ds_read_b128 v[4:7], v12 offset:16
	ds_read2_b32 v[22:23], v19 offset0:34 offset1:51
	ds_read_b128 v[8:11], v12 offset:32
	ds_read_b128 v[12:15], v12 offset:48
	ds_read2_b32 v[24:25], v19 offset0:68 offset1:85
	s_waitcnt lgkmcnt(5)
	v_fma_f32 v20, v0, v20, 0
	v_fmac_f32_e32 v20, v1, v21
	ds_read2_b32 v[0:1], v19 offset0:102 offset1:119
	s_waitcnt lgkmcnt(4)
	v_fmac_f32_e32 v20, v2, v22
	v_fmac_f32_e32 v20, v3, v23
	ds_read2_b32 v[2:3], v19 offset0:136 offset1:153
	s_waitcnt lgkmcnt(2)
	v_fmac_f32_e32 v20, v4, v24
	v_fmac_f32_e32 v20, v5, v25
	ds_read2_b32 v[4:5], v19 offset0:170 offset1:187
	s_waitcnt lgkmcnt(2)
	v_fmac_f32_e32 v20, v6, v0
	v_fmac_f32_e32 v20, v7, v1
	ds_read2_b32 v[0:1], v19 offset0:204 offset1:221
	s_waitcnt lgkmcnt(2)
	v_fmac_f32_e32 v20, v8, v2
	v_or_b32_e32 v2, 15, v28
	v_fmac_f32_e32 v20, v9, v3
	v_mad_u64_u32 v[2:3], s[0:1], v2, s5, v[16:17]
	s_waitcnt lgkmcnt(1)
	v_fmac_f32_e32 v20, v10, v4
	ds_read_b32 v3, v18 offset:18360
	ds_read_b32 v2, v2 offset:17408
	v_fmac_f32_e32 v20, v11, v5
	s_waitcnt lgkmcnt(2)
	v_fmac_f32_e32 v20, v12, v0
	v_fmac_f32_e32 v20, v13, v1
	s_waitcnt lgkmcnt(1)
	v_fmac_f32_e32 v20, v14, v3
	s_waitcnt lgkmcnt(0)
	v_fmac_f32_e32 v20, v15, v2
	v_xor_b32_e32 v0, 0x80000000, v20
	v_add3_u32 v1, v17, v26, v27
	ds_write_b32 v1, v0
	v_ashrrev_i32_e32 v1, 5, v82
	s_waitcnt lgkmcnt(0)
	s_barrier
; #define LDS_BARRIER() do { asm volatile("s_waitcnt lgkmcnt(0)" ::: "memory"); __builtin_amdgcn_s_barrier(); asm volatile("" ::: "memory"); } while (0)
; __device__ __forceinline__ void phase_dnprep(h16* Pdn, const h16* halo, const float* bd, const float* convw, const float* a_log, const float* dt_bias,
;                              h16* Tg, h16* qkg, float* gcg, float* betag, float* s2g, LAS unsigned char* ldsl, unsigned char* ldsb) {
;     ...
;         {
;             float zv[2];
; #pragma unroll
;             for (int it = 0; it < 2; ++it) {
;                 const int e = tl + 512 * it, r = e >> 5, c = e & 31;
;                 float sacc = 0.f;
; #pragma unroll
;                 for (int k = 0; k < 32; ++k) sacc += Mm[(32 + r) * 68 + k] * X[k * 68 + c];
;                 zv[it] = sacc;
;             }
; #pragma unroll
;             for (int it = 0; it < 2; ++it) { const int e = tl + 512 * it, r = e >> 5, c = e & 31; Zs[r * 33 + c] = zv[it]; }
;         }
;         LDS_BARRIER();
; #pragma unroll
;         for (int it = 0; it < 2; ++it) {
;             const int e = tl + 512 * it, r = e >> 5, c = e & 31;
;             float sacc = 0.f;
; #pragma unroll
;             for (int m = 0; m < 32; ++m) sacc += X[(32 + r) * 68 + 32 + m] * Zs[m * 33 + c];
;             X[(32 + r) * 68 + c] = -sacc;
;         }
;         LDS_BARRIER();
	v_and_b32_e32 v2, 15, v82
	v_bfe_u32 v3, v82, 4, 2
	v_bfe_u32 v4, v82, 6, 1
	v_bfe_u32 v5, v82, 7, 1
	v_lshl_add_u32 v8, v5, 4, v2
	v_add_u32_e32 v8, 32, v8
	v_mul_u32_u24_e32 v8, 0x110, v8
	v_lshl_add_u32 v8, v3, 2, v8
	v_add_u32_e32 v8, s3, v8
	v_lshl_add_u32 v28, v4, 4, v2
	v_mul_u32_u24_e32 v9, 0x110, v3
	v_lshl_add_u32 v9, v28, 2, v9
	v_add_u32_e32 v9, s78, v9
	ds_read_b32 v10, v8
	ds_read_b32 v11, v8 offset:16
	ds_read_b32 v12, v8 offset:32
	ds_read_b32 v13, v8 offset:48
	ds_read_b32 v14, v8 offset:64
	ds_read_b32 v15, v8 offset:80
	ds_read_b32 v16, v8 offset:96
	ds_read_b32 v17, v8 offset:112
	ds_read_b32 v18, v9
	ds_read_b32 v19, v9 offset:1088
	ds_read_b32 v20, v9 offset:2176
	ds_read_b32 v21, v9 offset:3264
	ds_read_b32 v22, v9 offset:4352
	ds_read_b32 v23, v9 offset:5440
	ds_read_b32 v24, v9 offset:6528
	ds_read_b32 v25, v9 offset:7616
	v_lshlrev_b32_e32 v26, 2, v3
	v_lshl_add_u32 v26, v5, 4, v26
	v_lshl_add_u32 v27, v26, 5, v26
	v_add_lshl_u32 v27, v27, v28, 2
	v_add_u32_e32 v27, s78, v27
	s_waitcnt lgkmcnt(0)
	v_mfma_f32_16x16x4_f32 v[36:39], v10, v18, 0
	v_mfma_f32_16x16x4_f32 v[36:39], v11, v19, v[36:39]
	v_mfma_f32_16x16x4_f32 v[36:39], v12, v20, v[36:39]
	v_mfma_f32_16x16x4_f32 v[36:39], v13, v21, v[36:39]
	v_mfma_f32_16x16x4_f32 v[36:39], v14, v22, v[36:39]
	v_mfma_f32_16x16x4_f32 v[36:39], v15, v23, v[36:39]
	v_mfma_f32_16x16x4_f32 v[36:39], v16, v24, v[36:39]
	v_mfma_f32_16x16x4_f32 v[36:39], v17, v25, v[36:39]
	s_nop 7
	s_nop 1
	ds_write_b32 v27, v36 offset:17408
	ds_write_b32 v27, v37 offset:17540
	ds_write_b32 v27, v38 offset:17672
	ds_write_b32 v27, v39 offset:17804
	s_waitcnt lgkmcnt(0)
	s_barrier
	v_lshl_add_u32 v8, v5, 4, v2
	v_add_u32_e32 v8, 32, v8
	v_mul_u32_u24_e32 v8, 0x110, v8
	v_lshl_add_u32 v8, v3, 2, v8
	v_add_u32_e32 v8, s78, v8
	v_lshl_add_u32 v9, v3, 5, v3
	v_add_lshl_u32 v9, v9, v28, 2
	v_add_u32_e32 v9, s78, v9
	ds_read_b32 v10, v8 offset:128
	ds_read_b32 v11, v8 offset:144
	ds_read_b32 v12, v8 offset:160
	ds_read_b32 v13, v8 offset:176
	ds_read_b32 v14, v8 offset:192
	ds_read_b32 v15, v8 offset:208
	ds_read_b32 v16, v8 offset:224
	ds_read_b32 v17, v8 offset:240
	ds_read_b32 v18, v9 offset:17408
	ds_read_b32 v19, v9 offset:17936
	ds_read_b32 v20, v9 offset:18464
	ds_read_b32 v21, v9 offset:18992
	ds_read_b32 v22, v9 offset:19520
	ds_read_b32 v23, v9 offset:20048
	ds_read_b32 v24, v9 offset:20576
	ds_read_b32 v25, v9 offset:21104
	v_add_u32_e32 v26, 32, v26
	v_mul_u32_u24_e32 v26, 0x110, v26
	v_lshl_add_u32 v26, v28, 2, v26
	v_add_u32_e32 v26, s78, v26
	s_waitcnt lgkmcnt(0)
	v_mfma_f32_16x16x4_f32 v[36:39], v10, v18, 0
	v_mfma_f32_16x16x4_f32 v[36:39], v11, v19, v[36:39]
	v_mfma_f32_16x16x4_f32 v[36:39], v12, v20, v[36:39]
	v_mfma_f32_16x16x4_f32 v[36:39], v13, v21, v[36:39]
	v_mfma_f32_16x16x4_f32 v[36:39], v14, v22, v[36:39]
	v_mfma_f32_16x16x4_f32 v[36:39], v15, v23, v[36:39]
	v_mfma_f32_16x16x4_f32 v[36:39], v16, v24, v[36:39]
	v_mfma_f32_16x16x4_f32 v[36:39], v17, v25, v[36:39]
	s_nop 7
	s_nop 1
	v_xor_b32_e32 v36, 0x80000000, v36
	v_xor_b32_e32 v37, 0x80000000, v37
	v_xor_b32_e32 v38, 0x80000000, v38
	v_xor_b32_e32 v39, 0x80000000, v39
	ds_write_b32 v26, v36
	ds_write_b32 v26, v37 offset:272
	ds_write_b32 v26, v38 offset:544
	ds_write_b32 v26, v39 offset:816
	v_readlane_b32 s0, v255, 22
	v_readlane_b32 s1, v255, 23
	v_ashrrev_i32_e32 v6, 3, v82
	v_and_b32_e32 v7, 7, v82
	v_mul_lo_u32 v0, v6, s4
	v_lshlrev_b32_e32 v1, 5, v7
	s_waitcnt lgkmcnt(0)
	s_barrier
	v_add3_u32 v3, s78, v0, v1
	ds_read_b96 v[0:2], v3
	ds_read2_b32 v[4:5], v3 offset0:3 offset1:4
	ds_read_b32 v8, v3 offset:28
	v_add_lshl_u32 v32, s26, v6, 6
	s_xor_b32 s39, s39, 1
	s_waitcnt lgkmcnt(2)
	v_cvt_pk_f16_f32 v1, v1, v2
	ds_read2_b32 v[2:3], v3 offset0:5 offset1:6
	v_cvt_f16_f32_e32 v0, v0
	s_waitcnt lgkmcnt(2)
	v_cvt_pk_f16_f32 v4, v4, v5
	s_waitcnt lgkmcnt(1)
	v_cvt_f16_f32_e32 v5, v8
	s_and_b64 vcc, exec, s[10:11]
	s_waitcnt lgkmcnt(0)
	v_cvt_pk_f16_f32 v3, v2, v3
	v_pack_b32_f16 v0, v0, v1
	v_alignbit_b32 v1, v4, v1, 16
	v_alignbit_b32 v2, v3, v4, 16
	v_alignbit_b32 v3, v5, v3, 16
	v_lshl_add_u64 v[4:5], v[32:33], 1, s[0:1]
	v_lshlrev_b32_e32 v32, 4, v7
	v_lshl_add_u64 v[4:5], v[4:5], 0, v[32:33]
	global_store_dwordx4 v[4:5], v[0:3], off
	s_waitcnt lgkmcnt(0)
	s_barrier
	s_cbranch_vccnz .LBB0_430
